# static s_setprio 1 for waves 4-7 for the whole kernel (on top of v27)
# speedup vs baseline: 1.0075x; 1.0075x over previous
; #define LAS __attribute__((address_space(3)))
; __global__ void __launch_bounds__(NTHR) mega_kernel(Params p) {
;   extern __shared__ __attribute__((aligned(16))) char smem[];
;   cg::grid_group grid = cg::this_grid();
;     ...
;   volatile LAS unsigned* st = (volatile LAS unsigned*)(smem + LDS_PHASE);
;   if (threadIdx.x == 0) { st[0] = 0u; st[1] = 0u; st[2] = 0u; st[3] = 0u; }
;   __syncthreads();
;   const XcdBarrier xb = xcd_barrier_post((unsigned*)(p.ws + OFF_BAR), st);
_Z11mega_kernel6Params:
	s_load_dwordx4 s[20:23], s[0:1], 0x100
	s_load_dwordx2 s[74:75], s[0:1], 0x110
	s_mov_b32 s50, s2
	s_add_u32 s2, s0, 0x110
	s_addc_u32 s3, s1, 0
	v_and_b32_e32 v167, 0x3ff, v0
	s_nop 1
	v_readfirstlane_b32 s32, v167
	s_nop 3
	s_cmpk_ge_u32 s32, 0x100
	s_cbranch_scc0 .Lgprio_skip
	s_setprio 1
.Lgprio_skip:
	v_writelane_b32 v252, s2, 0
	v_cmp_eq_u32_e64 s[4:5], 0, v167
	s_nop 0
	v_writelane_b32 v252, s3, 1
	s_mov_b64 s[2:3], exec
	v_writelane_b32 v252, s4, 2
	s_nop 1
	v_writelane_b32 v252, s5, 3
	s_and_b64 s[4:5], s[2:3], s[4:5]
	s_mov_b64 exec, s[4:5]
	s_cbranch_execz .LBB0_2
	s_add_i32 s4, 0, 0x24000
	v_mov_b32_e32 v1, 0
	v_mov_b32_e32 v2, s4
	s_add_i32 s4, 0, 0x24004
	ds_write_b32 v2, v1
	v_mov_b32_e32 v2, s4
	s_add_i32 s4, 0, 0x24008
	ds_write_b32 v2, v1
	v_mov_b32_e32 v2, s4
	s_add_i32 s4, 0, 0x2400c
	ds_write_b32 v2, v1
	v_mov_b32_e32 v2, s4
	ds_write_b32 v2, v1
